# v59 + attention VALU trim: pass-constant bias row offset folded into the per-lane addresses (-8 VALU/block) and -inf bias column replacing per-block masking (-9 VALU/block)
# speedup vs baseline: 1.0077x; 1.0077x over previous
; #define LAS __attribute__((address_space(3)))
; __device__ __forceinline__ void attn_phase(const bf16* __restrict__ proj, const bf16* __restrict__ vt, bf16* __restrict__ ya, const float* __restrict__ rpb, int T, int vcu, int G, LAS unsigned char* lds) {
;     ...
;     LAS float* tbl = (LAS float*)lds;
;     for (int idx = wave * 64 + lane; idx < 8 * 15 * 31; idx += NTHR) tbl[idx] = rpb[idx] * LOG2E;
;     __syncthreads();
.LBB0_464:
	s_or_b64 exec, exec, s[18:19]
	s_mov_b32 s18, 4
	v_mov_b32_e32 v1, v222
	s_waitcnt lgkmcnt(0)
	s_barrier
	s_xor_b64 s[4:5], s[20:21], -1
	v_readfirstlane_b32 s34, v1
	s_xor_b64 s[42:43], s[0:1], -1
	s_movk_i32 s0, 0xffc0
	v_mov_b32_e32 v2, s34
	v_writelane_b32 v253, s4, 30
	v_bfi_b32 v2, s0, v2, v1
	s_movk_i32 s0, 0xe88
	v_writelane_b32 v253, s5, 31
	v_cmp_gt_i32_e32 vcc, s0, v2
	s_and_saveexec_b64 s[0:1], vcc
	s_cbranch_execz .LBB0_472
	s_ashr_i32 s19, s18, 31
	s_lshl_b64 s[18:19], s[18:19], 3
	s_add_u32 s18, s74, s18
	s_addc_u32 s19, s75, s19
	s_load_dwordx2 s[18:19], s[18:19], 0x0
	s_mul_i32 s35, s52, 0x3a20
	s_mov_b32 s22, 0x8421085
	v_mov_b32_e32 v4, v2
	s_waitcnt lgkmcnt(0)
	s_add_u32 s18, s18, s35
	s_addc_u32 s19, s19, 0
	s_nop 1
.Ltbl_fill:
	v_lshlrev_b32_e32 v5, 2, v4
	global_load_dword v6, v5, s[18:19]
	v_mul_hi_u32 v7, v4, s22
	v_add_u32_e32 v5, v4, v7
	v_lshlrev_b32_e32 v5, 2, v5
	v_add_u32_e32 v4, 0x200, v4
	s_waitcnt vmcnt(0)
	v_mul_f32_e32 v6, 0x3fb8aa3b, v6
	ds_write_b32 v5, v6
	v_cmp_gt_u32_e32 vcc, 0xe88, v4
	s_and_b64 exec, exec, vcc
	s_cbranch_execnz .Ltbl_fill
	s_or_b64 exec, exec, s[0:1]
	v_cmp_gt_u32_e32 vcc, 0x78, v2
	s_and_saveexec_b64 s[22:23], vcc
	v_lshlrev_b32_e32 v5, 7, v2
	v_add_u32_e32 v5, 0x7c, v5
	v_mov_b32_e32 v6, 0xff800000
	ds_write_b32 v5, v6
	s_or_b64 exec, exec, s[22:23]

; __device__ __forceinline__ void attn_phase(const bf16* __restrict__ proj, const bf16* __restrict__ vt, bf16* __restrict__ ya, const float* __restrict__ rpb, int T, int vcu, int G, LAS unsigned char* lds) {
;     ...
;     const int n = lane & 15, q4 = lane >> 4, c = wave & 3, q0 = c * 16, cs = (c == 0) ? 0 : (c == 1) ? 8 : (c == 2) ? 24 : 32;
;     const float SC = 0.125f * LOG2E;
;     const unsigned qlane = (unsigned)(n * PW + 8 * q4) * 2u, klane = (unsigned)((8 * (n >> 2) + (n & 3)) * PW + 8 * q4) * 2u, vlane = (unsigned)(n * MC + 8 * q4) * 2u, olane = (unsigned)(n * AW + 4 * q4) * 2u;
;     unsigned dpack0 = 0u, dpack1 = 0u, vmask = 0u;
;     { const int qj = q0 + n; int js = qj - 8; js = js < 0 ? 0 : js; js = js > 48 ? 48 : js;
; #pragma unroll
;       for (int hf = 0; hf < 2; ++hf)
; #pragma unroll
;           for (int j = 0; j < 4; ++j) { const int kj = cs + 8 * q4 + 4 * hf + j; const bool v = (kj >= js) && (kj < js + 16); int dc = kj - qj + 15; dc = dc < 0 ? 0 : dc; dc = dc > 30 ? 30 : dc;
;               if (hf == 0) dpack0 |= (unsigned)dc << (8 * j); else dpack1 |= (unsigned)dc << (8 * j); vmask |= (v ? 1u : 0u) << (hf * 4 + j); } }
;     asm volatile("" : "+v"(dpack0), "+v"(dpack1), "+v"(vmask));
.LBB0_477:
	v_and_b32_e32 v2, 15, v1
	s_lshl_b32 s18, s1, 4
	v_lshrrev_b32_e32 v3, 1, v1
	v_or_b32_e32 v5, s18, v2
	v_and_b32_e32 v4, 24, v3
	v_med3_u32 v3, v5, 8, 56
	v_add_u32_e32 v6, -8, v3
	v_add_u32_e32 v7, s0, v4
	v_add_u32_e32 v8, 8, v3
	v_cmp_ge_u32_e32 vcc, v7, v6
	v_cmp_lt_u32_e64 s[38:39], v7, v8
	v_or_b32_e32 v10, 1, v7
	v_sub_u32_e32 v3, v7, v5
	s_and_b64 s[22:23], vcc, s[38:39]
	v_cmp_ge_u32_e32 vcc, v10, v6
	v_cmp_lt_u32_e64 s[38:39], v10, v8
	v_sub_u32_e32 v10, v10, v5
	v_med3_i32 v3, v3, -15, 15
	v_med3_i32 v10, v10, -15, 15
	v_mov_b32_e32 v13, 0xf00
	v_add_u32_e32 v3, 15, v3
	v_cndmask_b32_e64 v9, 0, 1, s[22:23]
	v_lshl_add_u32 v10, v10, 8, v13
	s_and_b64 s[22:23], vcc, s[38:39]
	v_or_b32_e32 v3, v10, v3
	v_cndmask_b32_e64 v10, 0, 2, s[22:23]
	v_or_b32_e32 v9, v10, v9
	v_or_b32_e32 v10, 2, v7
	v_cmp_ge_u32_e32 vcc, v10, v6
	v_cmp_lt_u32_e64 s[38:39], v10, v8
	v_or_b32_e32 v12, 3, v7
	v_sub_u32_e32 v10, v10, v5
	s_and_b64 s[22:23], vcc, s[38:39]
	v_cmp_ge_u32_e32 vcc, v12, v6
	v_cmp_lt_u32_e64 s[38:39], v12, v8
	v_sub_u32_e32 v12, v12, v5
	v_med3_i32 v10, v10, -15, 15
	v_mov_b32_e32 v14, 0xf0000
	v_med3_i32 v12, v12, -15, 15
	v_mov_b32_e32 v15, 0xf000000
	v_lshl_add_u32 v10, v10, 16, v14
	v_cndmask_b32_e64 v11, 0, 4, s[22:23]
	v_lshl_add_u32 v12, v12, 24, v15
	s_and_b64 s[22:23], vcc, s[38:39]
	v_or3_b32 v3, v3, v10, v12
	v_cndmask_b32_e64 v10, 0, 8, s[22:23]
	v_or3_b32 v9, v9, v11, v10
	v_or_b32_e32 v10, 4, v7
	v_cmp_ge_u32_e32 vcc, v10, v6
	v_cmp_lt_u32_e64 s[38:39], v10, v8
	v_or_b32_e32 v12, 5, v7
	v_sub_u32_e32 v10, v10, v5
	s_and_b64 s[22:23], vcc, s[38:39]
	v_cmp_ge_u32_e32 vcc, v12, v6
	v_cmp_lt_u32_e64 s[38:39], v12, v8
	v_sub_u32_e32 v12, v12, v5
	v_med3_i32 v10, v10, -15, 15
	v_med3_i32 v12, v12, -15, 15
	v_add_u32_e32 v10, 15, v10
	v_cndmask_b32_e64 v11, 0, 16, s[22:23]
	v_lshl_add_u32 v12, v12, 8, v13
	s_and_b64 s[22:23], vcc, s[38:39]
	v_or_b32_e32 v10, v12, v10
	v_cndmask_b32_e64 v12, 0, 32, s[22:23]
	v_or3_b32 v9, v9, v11, v12
	v_or_b32_e32 v11, 6, v7
	v_cmp_ge_u32_e32 vcc, v11, v6
	v_cmp_lt_u32_e64 s[38:39], v11, v8
	v_or_b32_e32 v7, 7, v7
	v_sub_u32_e32 v11, v11, v5
	s_and_b64 s[22:23], vcc, s[38:39]
	v_cmp_ge_u32_e32 vcc, v7, v6
	v_cmp_lt_u32_e64 s[38:39], v7, v8
	v_sub_u32_e32 v5, v7, v5
	v_med3_i32 v11, v11, -15, 15
	v_med3_i32 v5, v5, -15, 15
	s_and_b64 vcc, vcc, s[38:39]
	v_mov_b32_e32 v6, 0x80
	v_readlane_b32 s4, v254, 9
	v_lshl_add_u32 v11, v11, 16, v14
	v_cndmask_b32_e64 v12, 0, 64, s[22:23]
	v_lshl_add_u32 v5, v5, 24, v15
	v_cndmask_b32_e32 v6, 0, v6, vcc
	v_readlane_b32 s5, v254, 10
	v_writelane_b32 v253, s42, 32
	v_or3_b32 v5, v10, v11, v5
	v_or3_b32 v6, v9, v12, v6
	s_andn2_b64 vcc, exec, s[4:5]
	v_writelane_b32 v253, s43, 33
	s_cbranch_vccnz .LBB0_563
	v_and_b32_e32 v7, 48, v1
	v_lshlrev_b32_e32 v8, 1, v2
	v_and_b32_e32 v1, 3, v1
	v_and_or_b32 v1, v8, 24, v1
	v_mul_u32_u24_e32 v1, 0x1200, v1
	v_or_b32_e32 v8, v1, v4
	v_lshlrev_b32_e32 v154, 1, v8
	v_mul_u32_u24_e32 v8, 0x1200, v2
	v_or_b32_e32 v9, v8, v4
	v_lshl_or_b32 v8, v2, 10, v4
	v_and_b32_e32 v4, 1, v6
	v_cmp_eq_u32_e64 s[38:39], 1, v4
	v_and_b32_e32 v4, 2, v6
	v_cmp_ne_u32_e64 s[40:41], 0, v4
	v_and_b32_e32 v4, 4, v6
	v_cmp_ne_u32_e64 s[42:43], 0, v4
	v_and_b32_e32 v4, 8, v6
	v_cmp_ne_u32_e64 s[44:45], 0, v4
	v_and_b32_e32 v4, 16, v6
	v_cmp_ne_u32_e64 s[46:47], 0, v4
	v_and_b32_e32 v4, 32, v6
	v_readlane_b32 s24, v254, 27
	v_cmp_ne_u32_e64 s[48:49], 0, v4
	v_and_b32_e32 v4, 64, v6
	v_lshlrev_b32_e32 v10, 1, v9
	s_ashr_i32 s22, s34, 5
	v_mov_b32_e32 v11, v0
	v_mov_b32_e32 v9, v0
	v_readlane_b32 s25, v254, 28
	v_cmp_ne_u32_e64 s[50:51], 0, v4
	v_and_b32_e32 v4, 0x80, v6
	s_and_b32 s34, s22, -8
	v_lshl_add_u64 v[156:157], s[66:67], 0, v[10:11]
	v_lshl_add_u64 v[158:159], s[24:25], 0, v[8:9]
	v_cmp_ne_u32_e64 s[52:53], 0, v4
	v_lshlrev_b32_sdwa v4, v230, v5 dst_sel:DWORD dst_unused:UNUSED_PAD src0_sel:DWORD src1_sel:BYTE_3
	v_lshlrev_b32_sdwa v6, v230, v5 dst_sel:DWORD dst_unused:UNUSED_PAD src0_sel:DWORD src1_sel:BYTE_2
	v_lshlrev_b32_sdwa v8, v230, v5 dst_sel:DWORD dst_unused:UNUSED_PAD src0_sel:DWORD src1_sel:BYTE_1
	v_lshlrev_b32_e32 v5, 2, v5
	v_lshlrev_b32_sdwa v9, v230, v3 dst_sel:DWORD dst_unused:UNUSED_PAD src0_sel:DWORD src1_sel:BYTE_3
	v_lshlrev_b32_sdwa v10, v230, v3 dst_sel:DWORD dst_unused:UNUSED_PAD src0_sel:DWORD src1_sel:BYTE_2
	v_lshlrev_b32_sdwa v11, v230, v3 dst_sel:DWORD dst_unused:UNUSED_PAD src0_sel:DWORD src1_sel:BYTE_1
	v_lshlrev_b32_e32 v3, 2, v3
	s_lshr_b32 s22, s22, 3
	s_movk_i32 s5, 0x380
	v_and_b32_e32 v5, 0x3fc, v5
	v_and_b32_e32 v3, 0x3fc, v3
	v_mov_b32_e32 v12, 0x7c
	v_cndmask_b32_e64 v3, v12, v3, s[38:39]
	v_cndmask_b32_e64 v11, v12, v11, s[40:41]
	v_cndmask_b32_e64 v10, v12, v10, s[42:43]
	v_cndmask_b32_e64 v9, v12, v9, s[44:45]
	v_cndmask_b32_e64 v5, v12, v5, s[46:47]
	v_cndmask_b32_e64 v8, v12, v8, s[48:49]
	v_cndmask_b32_e64 v6, v12, v6, s[50:51]
	v_cndmask_b32_e64 v4, v12, v4, s[52:53]
	s_mulk_i32 s22, 0x400
	v_lshl_or_b32 v160, v1, 1, v7
	v_add_u32_e32 v1, s5, v4
	v_add_u32_e32 v178, s5, v6
	v_add_u32_e32 v179, s5, v8
	v_add_u32_e32 v186, s5, v5
	v_add_u32_e32 v187, s5, v9
	v_add_u32_e32 v188, s5, v10
	v_add_u32_e32 v189, s5, v11
	v_add_u32_e32 v190, s5, v3
	v_subrev_u32_e32 v4, s22, v4
	s_movk_i32 s5, 0x200
	v_subrev_u32_e32 v3, s22, v3
	s_mov_b32 s1, s37
	v_add_u32_e32 v191, s5, v4
	v_subrev_u32_e32 v4, s22, v6
	v_add_u32_e32 v192, s5, v4
	v_subrev_u32_e32 v4, s22, v8
	v_add_u32_e32 v193, s5, v4
	v_subrev_u32_e32 v4, s22, v5
	v_add_u32_e32 v194, s5, v4
	v_subrev_u32_e32 v4, s22, v9
	v_add_u32_e32 v195, s5, v4
	v_subrev_u32_e32 v4, s22, v10
	v_add_u32_e32 v196, s5, v4
	v_subrev_u32_e32 v4, s22, v11
	v_add_u32_e32 v198, s5, v3
	v_lshl_or_b32 v2, v2, 16, v7
	v_mov_b32_e32 v3, v0
	s_mov_b32 s4, s70
	s_mov_b32 s19, s37
	v_mov_b32_e32 v155, v0
	v_mov_b32_e32 v161, v0
	v_add_u32_e32 v197, s5, v4
	s_or_b32 s35, s34, 3
	v_lshl_add_u64 v[162:163], s[0:1], 1, v[2:3]
	v_readlane_b32 s1, v252, 0
; #define LAS __attribute__((address_space(3)))
; __device__ __forceinline__ void attn_phase(const bf16* __restrict__ proj, const bf16* __restrict__ vt, bf16* __restrict__ ya, const float* __restrict__ rpb, int T, int vcu, int G, LAS unsigned char* lds) {
;     ...
;     for (int wt = vcu; wt < 256; wt += G) {
;         const int rgp = wt % nrgp, h = (wt / nrgp) & 7, s = wt / (nrgp * 8), rg = rgp * 2 + (wave >> 2);
;         const LAS float* tbh = tbl + h * 15 * 31;
;         for (int pass = 0; pass < 2; ++pass) {
;             const int i0 = rg * 8 + pass * 4;
;             int rsj[4];
; #pragma unroll
;             for (int j = 0; j < 4; ++j) { int r_ = i0 + j - 4; r_ = r_ < 0 ? 0 : r_; r_ = r_ > rows - 8 ? rows - 8 : r_; rsj[j] = r_; }
;             const int ka0 = rsj[0], ka1 = rsj[3] + 7;
;             const size_t tok0 = (size_t)s * T;
;             bf16x8 qf[4][2];
; #pragma unroll
;             for (int j = 0; j < 4; ++j) { const char* qb = (const char*)(proj + (tok0 + (size_t)(i0 + j) * 64 + q0) * PW + C_Q + h * 64); qf[j][0] = *(const bf16x8*)(qb + qlane); qf[j][1] = *(const bf16x8*)(qb + qlane + 64); }
;             const char* kb = (const char*)(proj + (tok0 + cs) * PW + C_K + h * 64);
;             const char* vb = (const char*)(vt + (size_t)(h * 64) * MC + tok0 + cs);
;             f32x4 o[4][4]; float mrun[4], lrun[4];
; #pragma unroll
;             for (int j = 0; j < 4; ++j) { mrun[j] = -INFINITY; lrun[j] = 0.f;
; #pragma unroll
.LBB0_479:
	s_abs_i32 s23, s1
	v_readlane_b32 s5, v253, 19
	s_mul_hi_u32 s24, s23, s5
	s_mul_i32 s25, s24, s85
	s_sub_i32 s25, s23, s25
	s_ashr_i32 s22, s1, 31
	s_add_i32 s30, s24, 1
	s_sub_i32 s31, s25, s85
	s_cmp_ge_u32 s25, s85
	s_cselect_b32 s24, s30, s24
	s_cselect_b32 s25, s31, s25
	s_add_i32 s30, s24, 1
	s_cmp_ge_u32 s25, s85
	s_cselect_b32 s24, s30, s24
	v_readlane_b32 s5, v253, 20
	s_xor_b32 s24, s24, s22
	s_mul_hi_u32 s25, s23, s5
	s_sub_i32 s60, s24, s22
	s_mul_i32 s30, s25, s86
	s_mul_i32 s24, s60, s85
	s_sub_i32 s23, s23, s30
	s_sub_i32 s24, s1, s24
	s_and_b32 s61, s60, 7
	s_add_i32 s30, s25, 1
	s_sub_i32 s31, s23, s86
	s_cmp_ge_u32 s23, s86
	s_cselect_b32 s25, s30, s25
	s_cselect_b32 s23, s31, s23
	s_add_i32 s30, s25, 1
	s_cmp_ge_u32 s23, s86
	s_cselect_b32 s23, s30, s25
	s_xor_b32 s23, s23, s22
	s_sub_i32 s70, s23, s22
	v_readlane_b32 s5, v253, 22
	s_lshl_b32 s80, s24, 4
	s_mul_i32 s24, s70, s5
	s_mul_hi_i32 s25, s70, s5
	s_or_b32 s30, s24, s0
	s_mul_i32 s31, s25, 0x2400
	s_mul_hi_u32 s74, s30, 0x2400
	s_add_i32 s80, s80, s34
	s_or_b64 s[22:23], s[24:25], s[18:19]
	s_lshl_b32 s36, s61, 7
	s_add_i32 s74, s74, s31
	s_mulk_i32 s30, 0x2400
	s_add_u32 s30, s66, s30
	s_addc_u32 s31, s67, s74
	s_add_u32 s30, s30, s36
	s_addc_u32 s31, s31, 0
	s_mul_i32 s71, s61, 0x780
	s_lshl_b32 s61, s61, 22
	v_lshl_add_u64 v[166:167], s[30:31], 0, v[154:155]
	s_lshl_b64 s[30:31], s[22:23], 10
	s_add_u32 s24, s0, s24
	v_lshl_add_u64 v[2:3], v[158:159], 0, s[36:37]
	s_addc_u32 s25, 0, s25
	v_lshl_add_u64 v[168:169], v[2:3], 0, s[30:31]
	s_mulk_i32 s25, 0x2400
	s_mul_hi_u32 s30, s24, 0x2400
	s_mulk_i32 s24, 0x2400
	s_add_i32 s25, s30, s25
	s_or_b32 s24, s24, s36
	v_lshl_add_u64 v[170:171], s[24:25], 0, v[160:161]
	s_mul_i32 s24, s85, 0x800
	s_mul_i32 s24, s24, s60
	s_add_i32 s24, s24, s71
	s_mul_i32 s25, s1, 0x800
	s_sub_i32 s24, s24, s25
	v_writelane_b32 v253, s24, 47
	s_lshl_b32 s24, s1, 4
	v_readlane_b32 s5, v253, 21
	s_add_i32 s24, s35, s24
	s_mul_i32 s25, s5, s60
	v_readlane_b32 s5, v253, 23
	s_sub_i32 s81, s24, s25
	s_mul_i32 s24, s5, s70
	s_mul_hi_i32 s25, s5, s70
	s_add_u32 s24, s61, s24
	s_addc_u32 s25, 0, s25
	v_lshl_add_u64 v[164:165], v[156:157], 0, s[36:37]
	v_writelane_b32 v253, s71, 46
	v_lshl_add_u64 v[172:173], s[24:25], 0, v[162:163]
	s_mov_b32 s76, 0
	s_mov_b64 s[70:71], -1
.LBB0_480:
	s_or_b32 s74, s76, s80
	s_max_i32 s24, s74, 4
	s_add_i32 s24, s24, -4
	s_or_b32 s30, s74, 3
	s_min_i32 s36, s24, s87
	s_max_i32 s24, s30, 4
	s_add_i32 s24, s24, -4
	s_or_b32 s82, s74, 1
	s_or_b32 s60, s74, 2
	s_min_i32 s89, s24, s87
	s_ashr_i32 s75, s74, 31
	s_ashr_i32 s83, s82, 31
	s_ashr_i32 s61, s60, 31
	s_ashr_i32 s31, s30, 31
	s_add_i32 s89, s89, 7
	v_mov_b32_e32 v5, 0
	s_cmp_gt_i32 s36, s89
	v_mov_b32_e32 v4, v5
	v_mov_b32_e32 v3, v5
	v_mov_b32_e32 v2, v5
	v_mov_b32_e32 v9, v5
	v_mov_b32_e32 v8, v5
	v_mov_b32_e32 v7, v5
	v_mov_b32_e32 v6, v5
	v_mov_b32_e32 v13, v5
	v_mov_b32_e32 v12, v5
	v_mov_b32_e32 v11, v5
	v_mov_b32_e32 v10, v5
	v_mov_b32_e32 v17, v5
	v_mov_b32_e32 v16, v5
	v_mov_b32_e32 v15, v5
	v_mov_b32_e32 v14, v5
	v_mov_b32_e32 v65, v5
	v_mov_b32_e32 v64, v5
	v_mov_b32_e32 v63, v5
	v_mov_b32_e32 v62, v5
	v_mov_b32_e32 v61, v5
	v_mov_b32_e32 v60, v5
	v_mov_b32_e32 v59, v5
	v_mov_b32_e32 v58, v5
	v_mov_b32_e32 v57, v5
	v_mov_b32_e32 v56, v5
	v_mov_b32_e32 v55, v5
	v_mov_b32_e32 v54, v5
	v_mov_b32_e32 v53, v5
	v_mov_b32_e32 v52, v5
	v_mov_b32_e32 v51, v5
	v_mov_b32_e32 v50, v5
	v_mov_b32_e32 v49, v5
	v_mov_b32_e32 v48, v5
	v_mov_b32_e32 v47, v5
	v_mov_b32_e32 v46, v5
	v_mov_b32_e32 v45, v5
	v_mov_b32_e32 v44, v5
	v_mov_b32_e32 v43, v5
	v_mov_b32_e32 v42, v5
	v_mov_b32_e32 v41, v5
	v_mov_b32_e32 v40, v5
	v_mov_b32_e32 v39, v5
	v_mov_b32_e32 v38, v5
	v_mov_b32_e32 v37, v5
	v_mov_b32_e32 v36, v5
	v_mov_b32_e32 v35, v5
	v_mov_b32_e32 v34, v5
	v_mov_b32_e32 v33, v5
	v_mov_b32_e32 v32, v5
	v_mov_b32_e32 v31, v5
	v_mov_b32_e32 v30, v5
	v_mov_b32_e32 v29, v5
	v_mov_b32_e32 v28, v5
	v_mov_b32_e32 v27, v5
	v_mov_b32_e32 v26, v5
	v_mov_b32_e32 v25, v5
	v_mov_b32_e32 v24, v5
	v_mov_b32_e32 v23, v5
	v_mov_b32_e32 v22, v5
	v_mov_b32_e32 v21, v5
	v_mov_b32_e32 v20, v5
	v_mov_b32_e32 v19, v5
	v_mov_b32_e32 v18, v5
	v_mov_b32_e32 v218, v5
	v_mov_b32_e32 v217, v5
	v_mov_b32_e32 v216, v5
	v_mov_b32_e32 v215, v5
	s_cbranch_scc1 .LBB0_559
; __device__ __forceinline__ void attn_phase(const bf16* __restrict__ proj, const bf16* __restrict__ vt, bf16* __restrict__ ya, const float* __restrict__ rpb, int T, int vcu, int G, LAS unsigned char* lds) {
;     ...
;             const int i0 = rg * 8 + pass * 4;
;             int rsj[4];
; #pragma unroll
;             for (int j = 0; j < 4; ++j) { int r_ = i0 + j - 4; r_ = r_ < 0 ? 0 : r_; r_ = r_ > rows - 8 ? rows - 8 : r_; rsj[j] = r_; }
;             const int ka0 = rsj[0], ka1 = rsj[3] + 7;
;             const size_t tok0 = (size_t)s * T;
;             bf16x8 qf[4][2];
; #pragma unroll
;             for (int j = 0; j < 4; ++j) { const char* qb = (const char*)(proj + (tok0 + (size_t)(i0 + j) * 64 + q0) * PW + C_Q + h * 64); qf[j][0] = *(const bf16x8*)(qb + qlane); qf[j][1] = *(const bf16x8*)(qb + qlane + 64); }
;             const char* kb = (const char*)(proj + (tok0 + cs) * PW + C_K + h * 64);
;             const char* vb = (const char*)(vt + (size_t)(h * 64) * MC + tok0 + cs);
;             f32x4 o[4][4]; float mrun[4], lrun[4];
; #pragma unroll
;             for (int j = 0; j < 4; ++j) { mrun[j] = -INFINITY; lrun[j] = 0.f;
; #pragma unroll
;                 for (int dt = 0; dt < 4; ++dt) o[j][dt] = (f32x4){0.f, 0.f, 0.f, 0.f}; }
;             bf16x8 kf[2][2]; v4u vf[4];
;             { const char* kp = kb + (size_t)ka0 * 64 * PW * 2;
; #pragma unroll
;               for (int hf = 0; hf < 2; ++hf) { kf[hf][0] = *(const bf16x8*)(kp + (size_t)(4 * hf) * PW * 2 + klane); kf[hf][1] = *(const bf16x8*)(kp + (size_t)(4 * hf) * PW * 2 + klane + 64); }
;             }
	s_max_i32 s24, s82, 4
	s_add_i32 s24, s24, -4
	s_min_i32 s77, s24, s87
	s_max_i32 s24, s60, 4
	s_add_i32 s24, s24, -4
	s_min_i32 s78, s24, s87
	s_lshl_b64 s[24:25], s[74:75], 6
	s_add_u32 s24, s24, s22
	s_addc_u32 s25, s25, s23
	s_mul_i32 s79, s25, 0x2400
	v_mad_u64_u32 v[2:3], s[24:25], s24, v231, v[164:165]
	s_lshl_b64 s[24:25], s[82:83], 6
	s_add_u32 s24, s24, s22
	v_add_u32_e32 v3, s79, v3
	s_addc_u32 s25, s25, s23
	global_load_dwordx4 v[66:69], v[2:3], off
	global_load_dwordx4 v[70:73], v[2:3], off offset:64
	s_mul_i32 s79, s25, 0x2400
	v_mad_u64_u32 v[2:3], s[24:25], s24, v231, v[164:165]
	s_lshl_b64 s[24:25], s[60:61], 6
	s_add_u32 s24, s24, s22
	v_add_u32_e32 v3, s79, v3
	s_addc_u32 s25, s25, s23
	global_load_dwordx4 v[74:77], v[2:3], off
	global_load_dwordx4 v[78:81], v[2:3], off offset:64
	s_mul_i32 s79, s25, 0x2400
	v_mad_u64_u32 v[2:3], s[24:25], s24, v231, v[164:165]
	s_lshl_b64 s[24:25], s[30:31], 6
	s_add_u32 s24, s24, s22
	v_add_u32_e32 v3, s79, v3
	s_addc_u32 s25, s25, s23
	global_load_dwordx4 v[82:85], v[2:3], off
	global_load_dwordx4 v[86:89], v[2:3], off offset:64
	s_mul_i32 s79, s25, 0x2400
	v_mad_u64_u32 v[2:3], s[24:25], s24, v231, v[164:165]
	v_add_u32_e32 v3, s79, v3
	global_load_dwordx4 v[90:93], v[2:3], off
	global_load_dwordx4 v[94:97], v[2:3], off offset:64
	v_mad_u64_u32 v[2:3], s[24:25], s36, v232, v[166:167]
	s_mov_b32 s24, 0x9000
	s_nop 0
	v_add_co_u32_e32 v4, vcc, s24, v2
	v_mad_u64_u32 v[174:175], s[24:25], s36, v232, v[170:171]
	s_nop 0
	v_addc_co_u32_e32 v5, vcc, 0, v3, vcc
	global_load_dwordx4 v[118:121], v[2:3], off offset:1024
	global_load_dwordx4 v[122:125], v[2:3], off offset:1088
	global_load_dwordx4 v[110:113], v[4:5], off offset:1088
	global_load_dwordx4 v[126:129], v[4:5], off offset:1024
	s_lshl_b32 s91, s36, 7
	s_mul_i32 s24, s74, 0xffffff80
	v_readlane_b32 s25, v253, 46
	s_nop 3
	s_add_i32 s24, s24, s25
	s_add_i32 s24, s24, s91
	v_add_u32_e32 v219, s24, v1
	v_add_u32_e32 v220, s24, v178
	v_add_u32_e32 v221, s24, v179
	v_add_u32_e32 v233, s24, v186
	v_add_u32_e32 v234, s24, v187
	v_add_u32_e32 v235, s24, v188
	v_add_u32_e32 v236, s24, v189
	v_add_u32_e32 v237, s24, v190
	s_mul_i32 s24, s76, 0xffffff80
	v_readlane_b32 s25, v253, 47
	s_nop 3
	s_add_i32 s24, s24, s25
	s_add_i32 s24, s24, s91
	v_add_u32_e32 v238, s24, v191
	v_add_u32_e32 v239, s24, v192
	v_add_u32_e32 v240, s24, v193
	v_add_u32_e32 v241, s24, v194
	v_add_u32_e32 v242, s24, v195
	v_add_u32_e32 v243, s24, v196
	v_add_u32_e32 v244, s24, v197
	v_add_u32_e32 v245, s24, v198
	s_add_i32 s24, s81, s76
	s_max_i32 s24, s24, 4
	s_add_i32 s24, s24, -4
	s_min_i32 s24, s24, s87
	s_sub_i32 s92, s36, s24
	s_lshl_b64 s[24:25], s[36:37], 7
	v_mov_b32_e32 v215, 0
	v_mov_b32_e32 v229, 0x260
	v_mov_b32_e32 v228, 0x3727c5ac
	s_mov_b32 s90, 0
	s_lshl_b32 s91, s36, 7
	s_sub_i32 s93, s36, s78
	s_sub_i32 s94, s36, s77
	v_lshl_add_u64 v[176:177], v[172:173], 0, s[24:25]
	v_lshl_add_u64 v[98:99], s[58:59], 0, v[176:177]
	s_mov_b32 s24, 0x1a000000
	v_add_co_u32_e32 v100, vcc, s24, v98
	s_nop 1
	v_addc_co_u32_e32 v101, vcc, 0, v99, vcc
	v_add_co_u32_e32 v102, vcc, 0x1a100000, v98
	s_nop 1
	v_addc_co_u32_e32 v103, vcc, 0, v99, vcc
	global_load_dwordx4 v[142:145], v[100:101], off
	global_load_dwordx4 v[134:137], v[102:103], off
	v_add_co_u32_e32 v100, vcc, 0x1a200000, v98
	s_nop 1
	v_addc_co_u32_e32 v101, vcc, 0, v99, vcc
	v_add_co_u32_e32 v98, vcc, 0x1a300000, v98
	s_nop 1
	v_addc_co_u32_e32 v99, vcc, 0, v99, vcc
	global_load_dwordx4 v[138:141], v[100:101], off
	global_load_dwordx4 v[130:133], v[98:99], off
	v_mov_b32_e32 v246, 0xff800000
	v_mov_b32_e32 v247, 0xff800000
	v_mov_b32_e32 v248, 0xff800000
	v_mov_b32_e32 v249, 0xff800000
	v_mov_b32_e32 v216, 0
	v_mov_b32_e32 v217, 0
	v_mov_b32_e32 v218, 0
	v_mov_b32_e32 v18, 0
	v_mov_b32_e32 v19, v215
	v_mov_b32_e32 v20, v215
	v_mov_b32_e32 v21, v215
	v_mov_b32_e32 v22, 0
	v_mov_b32_e32 v23, v215
	v_mov_b32_e32 v24, v215
	v_mov_b32_e32 v25, v215
	v_mov_b32_e32 v26, 0
	v_mov_b32_e32 v27, v215
	v_mov_b32_e32 v28, v215
	v_mov_b32_e32 v29, v215
	v_mov_b32_e32 v30, 0
	v_mov_b32_e32 v31, v215
	v_mov_b32_e32 v32, v215
	v_mov_b32_e32 v33, v215
	v_mov_b32_e32 v34, 0
	v_mov_b32_e32 v35, v215
	v_mov_b32_e32 v36, v215
	v_mov_b32_e32 v37, v215
	v_mov_b32_e32 v38, 0
	v_mov_b32_e32 v39, v215
	v_mov_b32_e32 v40, v215
	v_mov_b32_e32 v41, v215
	v_mov_b32_e32 v42, 0
	v_mov_b32_e32 v43, v215
	v_mov_b32_e32 v44, v215
	v_mov_b32_e32 v45, v215
	v_mov_b32_e32 v46, 0
	v_mov_b32_e32 v47, v215
	v_mov_b32_e32 v48, v215
	v_mov_b32_e32 v49, v215
	v_mov_b32_e32 v50, 0
	v_mov_b32_e32 v51, v215
	v_mov_b32_e32 v52, v215
	v_mov_b32_e32 v53, v215
	v_mov_b32_e32 v54, 0
	v_mov_b32_e32 v55, v215
	v_mov_b32_e32 v56, v215
	v_mov_b32_e32 v57, v215
	v_mov_b32_e32 v58, 0
	v_mov_b32_e32 v59, v215
	v_mov_b32_e32 v60, v215
	v_mov_b32_e32 v61, v215
	v_mov_b32_e32 v62, 0
	v_mov_b32_e32 v63, v215
	v_mov_b32_e32 v64, v215
	v_mov_b32_e32 v65, v215
	v_mov_b32_e32 v14, 0
	v_mov_b32_e32 v15, v215
	v_mov_b32_e32 v16, v215
	v_mov_b32_e32 v17, v215
	v_mov_b32_e32 v10, 0
	v_mov_b32_e32 v11, v215
	v_mov_b32_e32 v12, v215
	v_mov_b32_e32 v13, v215
	v_mov_b32_e32 v6, 0
	v_mov_b32_e32 v7, v215
	v_mov_b32_e32 v8, v215
	v_mov_b32_e32 v9, v215
	v_mov_b32_e32 v2, 0
	v_mov_b32_e32 v3, v215
	v_mov_b32_e32 v4, v215
	v_mov_b32_e32 v5, v215

; __device__ __forceinline__ unsigned cvt_pk_bf16(float lo, float hi) { unsigned r; asm volatile("v_cvt_pk_bf16_f32 %0, %1, %2" : "=v"(r) : "v"(lo), "v"(hi)); return r; }
; __device__ __forceinline__ void attn_phase(const bf16* __restrict__ proj, const bf16* __restrict__ vt, bf16* __restrict__ ya, const float* __restrict__ rpb, int T, int vcu, int G, LAS unsigned char* lds) {
;     ...
;                 for (int j = 0; j < 4; ++j) { const int kr = ka - rsj[j];
;                     if (kr >= 0 && kr < 8) {
;                         f32x4 st[2];
; #pragma unroll
;                         for (int hf = 0; hf < 2; ++hf) { const f32x4 t = __builtin_amdgcn_mfma_f32_16x16x32_bf16(kf[hf][0], qf[j][0], (f32x4){0.f, 0.f, 0.f, 0.f}, 0, 0, 0);
;                             st[hf] = __builtin_amdgcn_mfma_f32_16x16x32_bf16(kf[hf][1], qf[j][1], t, 0, 0, 0); }
;                         const LAS float* tb = tbh + (ka - i0 - j + 7) * 31;
;                         float mloc = -INFINITY;
; #pragma unroll
;                         for (int hf = 0; hf < 2; ++hf)
; #pragma unroll
;                             for (int e = 0; e < 4; ++e) { const unsigned dc = ((hf == 0 ? dpack0 : dpack1) >> (8 * e)) & 0xffu; const float b = tb[dc];
;                                 const float v = ((vmask >> (hf * 4 + e)) & 1u) ? st[hf][e] * SC + b : -INFINITY; st[hf][e] = v; mloc = fmaxf(mloc, v); }
;                         mloc = fmaxf(mloc, __shfl_xor(mloc, 16)); mloc = fmaxf(mloc, __shfl_xor(mloc, 32));
;                         const float mnew = fmaxf(mrun[j], mloc), alpha = __builtin_amdgcn_exp2f(mrun[j] - mnew); mrun[j] = mnew;
;                         float p[8], psum = 0.f;
; #pragma unroll
;                         for (int hf = 0; hf < 2; ++hf)
; #pragma unroll
;                             for (int e = 0; e < 4; ++e) { p[hf * 4 + e] = __builtin_amdgcn_exp2f(st[hf][e] - mnew); psum += p[hf * 4 + e]; }
;                         lrun[j] = lrun[j] * alpha + psum;
;                         v4u w; w.x = cvt_pk_bf16(p[0], p[1]); w.y = cvt_pk_bf16(p[2], p[3]); w.z = cvt_pk_bf16(p[4], p[5]); w.w = cvt_pk_bf16(p[6], p[7]);
;                         const bf16x8 pk = __builtin_bit_cast(bf16x8, w);
; #pragma unroll
;                         for (int dt = 0; dt < 4; ++dt) o[j][dt] = __builtin_amdgcn_mfma_f32_16x16x32_bf16(__builtin_bit_cast(bf16x8, vf[dt]), pk, o[j][dt] * alpha, 0, 0, 0);
.LBB0_485:
	ds_read_b32 v251, v237
	ds_read_b32 v250, v236
	ds_read_b32 v227, v235
	ds_read_b32 v226, v234
	ds_read_b32 v199, v233
	ds_read_b32 v212, v221
	ds_read_b32 v213, v220
	ds_read_b32 v214, v219
	s_waitcnt vmcnt(15)
	v_mfma_f32_16x16x32_bf16 v[146:149], v[118:121], v[66:69], 0
	s_waitcnt vmcnt(14)
	v_mfma_f32_16x16x32_bf16 v[150:153], v[122:125], v[70:73], v[146:149]
	s_waitcnt vmcnt(12)
	v_mfma_f32_16x16x32_bf16 v[146:149], v[126:129], v[66:69], 0
	v_mfma_f32_16x16x32_bf16 v[146:149], v[110:113], v[70:73], v[146:149]
	s_nop 6
	s_waitcnt lgkmcnt(0)
	v_fmamk_f32 v150, v150, 0x3e38aa3b, v251
	v_fmamk_f32 v151, v151, 0x3e38aa3b, v250
	v_fmamk_f32 v152, v152, 0x3e38aa3b, v227
	v_fmamk_f32 v153, v153, 0x3e38aa3b, v226
	v_fmamk_f32 v146, v146, 0x3e38aa3b, v199
	v_fmamk_f32 v147, v147, 0x3e38aa3b, v212
	v_fmamk_f32 v148, v148, 0x3e38aa3b, v213
	v_fmamk_f32 v149, v149, 0x3e38aa3b, v214
	v_max3_f32 v225, v150, v151, v152
	v_max3_f32 v225, v225, v153, v146
	v_max3_f32 v225, v225, v147, v148
	v_max_f32_e32 v225, v225, v149
	v_mov_b32_e32 v226, v225
	s_nop 1
	v_permlane16_swap_b32_e32 v225, v226
	v_max_f32_e32 v225, v225, v226
	v_mov_b32_e32 v226, v225
	s_nop 1
	v_permlane32_swap_b32_e32 v225, v226
	v_max3_f32 v225, v249, v225, v226
	v_sub_f32_e32 v250, v249, v225
	v_sub_f32_e32 v150, v150, v225
	v_sub_f32_e32 v151, v151, v225
	v_sub_f32_e32 v152, v152, v225
	v_sub_f32_e32 v153, v153, v225
	v_sub_f32_e32 v146, v146, v225
	v_sub_f32_e32 v147, v147, v225
	v_sub_f32_e32 v148, v148, v225
	v_sub_f32_e32 v149, v149, v225
	v_exp_f32_e32 v250, v250
	v_exp_f32_e32 v150, v150
	v_exp_f32_e32 v151, v151
	v_exp_f32_e32 v152, v152
	v_exp_f32_e32 v153, v153
	v_exp_f32_e32 v146, v146
	v_exp_f32_e32 v147, v147
	v_exp_f32_e32 v148, v148
	v_exp_f32_e32 v149, v149
	v_mov_b32_e32 v249, v225
	v_add_f32_e32 v226, v150, v151
	v_add_f32_e32 v226, v226, v152
	v_add_f32_e32 v226, v226, v153
	v_add_f32_e32 v226, v226, v146
	v_add_f32_e32 v226, v226, v147
	v_add_f32_e32 v226, v226, v148
	v_add_f32_e32 v226, v226, v149
	v_fma_f32 v218, v218, v250, v226
	v_pk_mul_f32 v[64:65], v[64:65], v[250:251] op_sel_hi:[1,0]
	v_pk_mul_f32 v[62:63], v[62:63], v[250:251] op_sel_hi:[1,0]
	v_pk_mul_f32 v[60:61], v[60:61], v[250:251] op_sel_hi:[1,0]
	v_pk_mul_f32 v[58:59], v[58:59], v[250:251] op_sel_hi:[1,0]
	v_pk_mul_f32 v[56:57], v[56:57], v[250:251] op_sel_hi:[1,0]
	v_pk_mul_f32 v[54:55], v[54:55], v[250:251] op_sel_hi:[1,0]
	v_pk_mul_f32 v[52:53], v[52:53], v[250:251] op_sel_hi:[1,0]
	v_pk_mul_f32 v[50:51], v[50:51], v[250:251] op_sel_hi:[1,0]
	v_cvt_pk_bf16_f32 v150, v150, v151
	v_cvt_pk_bf16_f32 v151, v152, v153
	v_cvt_pk_bf16_f32 v152, v146, v147
	v_cvt_pk_bf16_f32 v153, v148, v149
	s_nop 1
	s_waitcnt vmcnt(11)
	v_mfma_f32_16x16x32_bf16 v[62:65], v[142:145], v[150:153], v[62:65]
	s_waitcnt vmcnt(10)
	v_mfma_f32_16x16x32_bf16 v[58:61], v[134:137], v[150:153], v[58:61]
	s_waitcnt vmcnt(9)
	v_mfma_f32_16x16x32_bf16 v[54:57], v[138:141], v[150:153], v[54:57]
	s_waitcnt vmcnt(8)
	v_mfma_f32_16x16x32_bf16 v[50:53], v[130:133], v[150:153], v[50:53]

; __device__ __forceinline__ unsigned cvt_pk_bf16(float lo, float hi) { unsigned r; asm volatile("v_cvt_pk_bf16_f32 %0, %1, %2" : "=v"(r) : "v"(lo), "v"(hi)); return r; }
; __device__ __forceinline__ void attn_phase(const bf16* __restrict__ proj, const bf16* __restrict__ vt, bf16* __restrict__ ya, const float* __restrict__ rpb, int T, int vcu, int G, LAS unsigned char* lds) {
;     ...
;                 for (int j = 0; j < 4; ++j) { const int kr = ka - rsj[j];
;                     if (kr >= 0 && kr < 8) {
;                         f32x4 st[2];
; #pragma unroll
;                         for (int hf = 0; hf < 2; ++hf) { const f32x4 t = __builtin_amdgcn_mfma_f32_16x16x32_bf16(kf[hf][0], qf[j][0], (f32x4){0.f, 0.f, 0.f, 0.f}, 0, 0, 0);
;                             st[hf] = __builtin_amdgcn_mfma_f32_16x16x32_bf16(kf[hf][1], qf[j][1], t, 0, 0, 0); }
;                         const LAS float* tb = tbh + (ka - i0 - j + 7) * 31;
;                         float mloc = -INFINITY;
; #pragma unroll
;                         for (int hf = 0; hf < 2; ++hf)
; #pragma unroll
;                             for (int e = 0; e < 4; ++e) { const unsigned dc = ((hf == 0 ? dpack0 : dpack1) >> (8 * e)) & 0xffu; const float b = tb[dc];
;                                 const float v = ((vmask >> (hf * 4 + e)) & 1u) ? st[hf][e] * SC + b : -INFINITY; st[hf][e] = v; mloc = fmaxf(mloc, v); }
;                         mloc = fmaxf(mloc, __shfl_xor(mloc, 16)); mloc = fmaxf(mloc, __shfl_xor(mloc, 32));
;                         const float mnew = fmaxf(mrun[j], mloc), alpha = __builtin_amdgcn_exp2f(mrun[j] - mnew); mrun[j] = mnew;
;                         float p[8], psum = 0.f;
; #pragma unroll
;                         for (int hf = 0; hf < 2; ++hf)
; #pragma unroll
;                             for (int e = 0; e < 4; ++e) { p[hf * 4 + e] = __builtin_amdgcn_exp2f(st[hf][e] - mnew); psum += p[hf * 4 + e]; }
;                         lrun[j] = lrun[j] * alpha + psum;
;                         v4u w; w.x = cvt_pk_bf16(p[0], p[1]); w.y = cvt_pk_bf16(p[2], p[3]); w.z = cvt_pk_bf16(p[4], p[5]); w.w = cvt_pk_bf16(p[6], p[7]);
;                         const bf16x8 pk = __builtin_bit_cast(bf16x8, w);
; #pragma unroll
;                         for (int dt = 0; dt < 4; ++dt) o[j][dt] = __builtin_amdgcn_mfma_f32_16x16x32_bf16(__builtin_bit_cast(bf16x8, vf[dt]), pk, o[j][dt] * alpha, 0, 0, 0);
.LBB0_505:
	ds_read_b32 v251, v245 offset:256
	ds_read_b32 v250, v244 offset:256
	ds_read_b32 v227, v243 offset:256
	ds_read_b32 v226, v242 offset:256
	ds_read_b32 v199, v241 offset:256
	ds_read_b32 v212, v240 offset:256
	ds_read_b32 v213, v239 offset:256
	ds_read_b32 v214, v238 offset:256
	s_waitcnt vmcnt(15)
	v_mfma_f32_16x16x32_bf16 v[146:149], v[118:121], v[74:77], 0
	s_waitcnt vmcnt(14)
	v_mfma_f32_16x16x32_bf16 v[150:153], v[122:125], v[78:81], v[146:149]
	s_waitcnt vmcnt(12)
	v_mfma_f32_16x16x32_bf16 v[146:149], v[126:129], v[74:77], 0
	v_mfma_f32_16x16x32_bf16 v[146:149], v[110:113], v[78:81], v[146:149]
	s_nop 6
	s_waitcnt lgkmcnt(0)
	v_fmamk_f32 v150, v150, 0x3e38aa3b, v251
	v_fmamk_f32 v151, v151, 0x3e38aa3b, v250
	v_fmamk_f32 v152, v152, 0x3e38aa3b, v227
	v_fmamk_f32 v153, v153, 0x3e38aa3b, v226
	v_fmamk_f32 v146, v146, 0x3e38aa3b, v199
	v_fmamk_f32 v147, v147, 0x3e38aa3b, v212
	v_fmamk_f32 v148, v148, 0x3e38aa3b, v213
	v_fmamk_f32 v149, v149, 0x3e38aa3b, v214
	v_max3_f32 v225, v150, v151, v152
	v_max3_f32 v225, v225, v153, v146
	v_max3_f32 v225, v225, v147, v148
	v_max_f32_e32 v225, v225, v149
	v_mov_b32_e32 v226, v225
	s_nop 1
	v_permlane16_swap_b32_e32 v225, v226
	v_max_f32_e32 v225, v225, v226
	v_mov_b32_e32 v226, v225
	s_nop 1
	v_permlane32_swap_b32_e32 v225, v226
	v_max3_f32 v225, v248, v225, v226
	v_sub_f32_e32 v250, v248, v225
	v_sub_f32_e32 v150, v150, v225
	v_sub_f32_e32 v151, v151, v225
	v_sub_f32_e32 v152, v152, v225
	v_sub_f32_e32 v153, v153, v225
	v_sub_f32_e32 v146, v146, v225
	v_sub_f32_e32 v147, v147, v225
	v_sub_f32_e32 v148, v148, v225
	v_sub_f32_e32 v149, v149, v225
	v_exp_f32_e32 v250, v250
	v_exp_f32_e32 v150, v150
	v_exp_f32_e32 v151, v151
	v_exp_f32_e32 v152, v152
	v_exp_f32_e32 v153, v153
	v_exp_f32_e32 v146, v146
	v_exp_f32_e32 v147, v147
	v_exp_f32_e32 v148, v148
	v_exp_f32_e32 v149, v149
	v_mov_b32_e32 v248, v225
	v_add_f32_e32 v226, v150, v151
	v_add_f32_e32 v226, v226, v152
	v_add_f32_e32 v226, v226, v153
	v_add_f32_e32 v226, v226, v146
	v_add_f32_e32 v226, v226, v147
	v_add_f32_e32 v226, v226, v148
	v_add_f32_e32 v226, v226, v149
	v_fma_f32 v217, v217, v250, v226
	v_pk_mul_f32 v[48:49], v[48:49], v[250:251] op_sel_hi:[1,0]
	v_pk_mul_f32 v[46:47], v[46:47], v[250:251] op_sel_hi:[1,0]
	v_pk_mul_f32 v[44:45], v[44:45], v[250:251] op_sel_hi:[1,0]
	v_pk_mul_f32 v[42:43], v[42:43], v[250:251] op_sel_hi:[1,0]
	v_pk_mul_f32 v[40:41], v[40:41], v[250:251] op_sel_hi:[1,0]
	v_pk_mul_f32 v[38:39], v[38:39], v[250:251] op_sel_hi:[1,0]
	v_pk_mul_f32 v[36:37], v[36:37], v[250:251] op_sel_hi:[1,0]
	v_pk_mul_f32 v[34:35], v[34:35], v[250:251] op_sel_hi:[1,0]
	v_cvt_pk_bf16_f32 v150, v150, v151
	v_cvt_pk_bf16_f32 v151, v152, v153
	v_cvt_pk_bf16_f32 v152, v146, v147
	v_cvt_pk_bf16_f32 v153, v148, v149
	s_nop 1
	s_waitcnt vmcnt(11)
	v_mfma_f32_16x16x32_bf16 v[46:49], v[142:145], v[150:153], v[46:49]
	s_waitcnt vmcnt(10)
	v_mfma_f32_16x16x32_bf16 v[42:45], v[134:137], v[150:153], v[42:45]
	s_waitcnt vmcnt(9)
	v_mfma_f32_16x16x32_bf16 v[38:41], v[138:141], v[150:153], v[38:41]
	s_waitcnt vmcnt(8)
	v_mfma_f32_16x16x32_bf16 v[34:37], v[130:133], v[150:153], v[34:37]
	s_add_i32 s24, s93, s90
	s_cmp_gt_u32 s24, 7
	s_cbranch_scc1 .LBB0_504
.LBB0_522:
	ds_read_b32 v251, v245 offset:128
	ds_read_b32 v250, v244 offset:128
	ds_read_b32 v227, v243 offset:128
	ds_read_b32 v226, v242 offset:128
	ds_read_b32 v199, v241 offset:128
	ds_read_b32 v212, v240 offset:128
	ds_read_b32 v213, v239 offset:128
	ds_read_b32 v214, v238 offset:128
	s_waitcnt vmcnt(15)
	v_mfma_f32_16x16x32_bf16 v[146:149], v[118:121], v[82:85], 0
	s_waitcnt vmcnt(14)
	v_mfma_f32_16x16x32_bf16 v[150:153], v[122:125], v[86:89], v[146:149]
	s_waitcnt vmcnt(12)
	v_mfma_f32_16x16x32_bf16 v[146:149], v[126:129], v[82:85], 0
	v_mfma_f32_16x16x32_bf16 v[146:149], v[110:113], v[86:89], v[146:149]
	s_nop 6
	s_waitcnt lgkmcnt(0)
	v_fmamk_f32 v150, v150, 0x3e38aa3b, v251
	v_fmamk_f32 v151, v151, 0x3e38aa3b, v250
	v_fmamk_f32 v152, v152, 0x3e38aa3b, v227
	v_fmamk_f32 v153, v153, 0x3e38aa3b, v226
	v_fmamk_f32 v146, v146, 0x3e38aa3b, v199
	v_fmamk_f32 v147, v147, 0x3e38aa3b, v212
	v_fmamk_f32 v148, v148, 0x3e38aa3b, v213
	v_fmamk_f32 v149, v149, 0x3e38aa3b, v214
	v_max3_f32 v225, v150, v151, v152
	v_max3_f32 v225, v225, v153, v146
	v_max3_f32 v225, v225, v147, v148
	v_max_f32_e32 v225, v225, v149
	v_mov_b32_e32 v226, v225
	s_nop 1
	v_permlane16_swap_b32_e32 v225, v226
	v_max_f32_e32 v225, v225, v226
	v_mov_b32_e32 v226, v225
	s_nop 1
	v_permlane32_swap_b32_e32 v225, v226
	v_max3_f32 v225, v247, v225, v226
	v_sub_f32_e32 v250, v247, v225
	v_sub_f32_e32 v150, v150, v225
	v_sub_f32_e32 v151, v151, v225
	v_sub_f32_e32 v152, v152, v225
	v_sub_f32_e32 v153, v153, v225
	v_sub_f32_e32 v146, v146, v225
	v_sub_f32_e32 v147, v147, v225
	v_sub_f32_e32 v148, v148, v225
	v_sub_f32_e32 v149, v149, v225
	v_exp_f32_e32 v250, v250
	v_exp_f32_e32 v150, v150
	v_exp_f32_e32 v151, v151
	v_exp_f32_e32 v152, v152
	v_exp_f32_e32 v153, v153
	v_exp_f32_e32 v146, v146
	v_exp_f32_e32 v147, v147
	v_exp_f32_e32 v148, v148
	v_exp_f32_e32 v149, v149
	v_mov_b32_e32 v247, v225
	v_add_f32_e32 v226, v150, v151
	v_add_f32_e32 v226, v226, v152
	v_add_f32_e32 v226, v226, v153
	v_add_f32_e32 v226, v226, v146
	v_add_f32_e32 v226, v226, v147
	v_add_f32_e32 v226, v226, v148
	v_add_f32_e32 v226, v226, v149
	v_fma_f32 v216, v216, v250, v226
	v_pk_mul_f32 v[32:33], v[32:33], v[250:251] op_sel_hi:[1,0]
	v_pk_mul_f32 v[30:31], v[30:31], v[250:251] op_sel_hi:[1,0]
	v_pk_mul_f32 v[28:29], v[28:29], v[250:251] op_sel_hi:[1,0]
	v_pk_mul_f32 v[26:27], v[26:27], v[250:251] op_sel_hi:[1,0]
	v_pk_mul_f32 v[24:25], v[24:25], v[250:251] op_sel_hi:[1,0]
	v_pk_mul_f32 v[22:23], v[22:23], v[250:251] op_sel_hi:[1,0]
	v_pk_mul_f32 v[20:21], v[20:21], v[250:251] op_sel_hi:[1,0]
	v_pk_mul_f32 v[18:19], v[18:19], v[250:251] op_sel_hi:[1,0]
	v_cvt_pk_bf16_f32 v150, v150, v151
	v_cvt_pk_bf16_f32 v151, v152, v153
	v_cvt_pk_bf16_f32 v152, v146, v147
	v_cvt_pk_bf16_f32 v153, v148, v149
	s_nop 1
	s_waitcnt vmcnt(11)
	v_mfma_f32_16x16x32_bf16 v[30:33], v[142:145], v[150:153], v[30:33]
	s_waitcnt vmcnt(10)
	v_mfma_f32_16x16x32_bf16 v[26:29], v[134:137], v[150:153], v[26:29]
	s_waitcnt vmcnt(9)
	v_mfma_f32_16x16x32_bf16 v[22:25], v[138:141], v[150:153], v[22:25]
	s_waitcnt vmcnt(8)
	v_mfma_f32_16x16x32_bf16 v[18:21], v[130:133], v[150:153], v[18:21]
	s_add_i32 s24, s92, s90
	s_cmp_gt_u32 s24, 7
	s_cbranch_scc1 .LBB0_556
; __device__ __forceinline__ void attn_phase(const bf16* __restrict__ proj, const bf16* __restrict__ vt, bf16* __restrict__ ya, const float* __restrict__ rpb, int T, int vcu, int G, LAS unsigned char* lds) {
;     ...
;                 for (int j = 0; j < 4; ++j) { const int kr = ka - rsj[j];
;                     if (kr >= 0 && kr < 8) {
;                         f32x4 st[2];
; #pragma unroll
;                         for (int hf = 0; hf < 2; ++hf) { const f32x4 t = __builtin_amdgcn_mfma_f32_16x16x32_bf16(kf[hf][0], qf[j][0], (f32x4){0.f, 0.f, 0.f, 0.f}, 0, 0, 0);
;                             st[hf] = __builtin_amdgcn_mfma_f32_16x16x32_bf16(kf[hf][1], qf[j][1], t, 0, 0, 0); }
;                         const LAS float* tb = tbh + (ka - i0 - j + 7) * 31;
;                         float mloc = -INFINITY;
; #pragma unroll
;                         for (int hf = 0; hf < 2; ++hf)
; #pragma unroll
;                             for (int e = 0; e < 4; ++e) { const unsigned dc = ((hf == 0 ? dpack0 : dpack1) >> (8 * e)) & 0xffu; const float b = tb[dc];
;                                 const float v = ((vmask >> (hf * 4 + e)) & 1u) ? st[hf][e] * SC + b : -INFINITY; st[hf][e] = v; mloc = fmaxf(mloc, v); }
;                         mloc = fmaxf(mloc, __shfl_xor(mloc, 16)); mloc = fmaxf(mloc, __shfl_xor(mloc, 32));
;                         const float mnew = fmaxf(mrun[j], mloc), alpha = __builtin_amdgcn_exp2f(mrun[j] - mnew); mrun[j] = mnew;
;                         float p[8], psum = 0.f;
; #pragma unroll
;                         for (int hf = 0; hf < 2; ++hf)
; #pragma unroll
;                             for (int e = 0; e < 4; ++e) { p[hf * 4 + e] = __builtin_amdgcn_exp2f(st[hf][e] - mnew); psum += p[hf * 4 + e]; }
;                         lrun[j] = lrun[j] * alpha + psum;
;                         v4u w; w.x = cvt_pk_bf16(p[0], p[1]); w.y = cvt_pk_bf16(p[2], p[3]); w.z = cvt_pk_bf16(p[4], p[5]); w.w = cvt_pk_bf16(p[6], p[7]);
;                         const bf16x8 pk = __builtin_bit_cast(bf16x8, w);
; #pragma unroll
;                         for (int dt = 0; dt < 4; ++dt) o[j][dt] = __builtin_amdgcn_mfma_f32_16x16x32_bf16(__builtin_bit_cast(bf16x8, vf[dt]), pk, o[j][dt] * alpha, 0, 0, 0);
;                     } }
; #pragma unroll
;                 for (int hf = 0; hf < 2; ++hf) { kf[hf][0] = kn[hf][0]; kf[hf][1] = kn[hf][1]; }
.LBB0_539:
	ds_read_b32 v251, v245
	ds_read_b32 v250, v244
	ds_read_b32 v227, v243
	ds_read_b32 v226, v242
	ds_read_b32 v199, v241
	ds_read_b32 v212, v240
	ds_read_b32 v213, v239
	ds_read_b32 v214, v238
	s_waitcnt vmcnt(15)
	v_mfma_f32_16x16x32_bf16 v[118:121], v[118:121], v[90:93], 0
	s_waitcnt vmcnt(14)
	v_mfma_f32_16x16x32_bf16 v[118:121], v[122:125], v[94:97], v[118:121]
	s_waitcnt vmcnt(12)
	v_mfma_f32_16x16x32_bf16 v[124:127], v[126:129], v[90:93], 0
	v_mfma_f32_16x16x32_bf16 v[110:113], v[110:113], v[94:97], v[124:127]
	s_nop 6
	s_waitcnt lgkmcnt(0)
	v_fmamk_f32 v118, v118, 0x3e38aa3b, v251
	v_fmamk_f32 v119, v119, 0x3e38aa3b, v250
	v_fmamk_f32 v120, v120, 0x3e38aa3b, v227
	v_fmamk_f32 v121, v121, 0x3e38aa3b, v226
	v_fmamk_f32 v110, v110, 0x3e38aa3b, v199
	v_fmamk_f32 v111, v111, 0x3e38aa3b, v212
	v_fmamk_f32 v112, v112, 0x3e38aa3b, v213
	v_fmamk_f32 v113, v113, 0x3e38aa3b, v214
	v_max3_f32 v225, v118, v119, v120
	v_max3_f32 v225, v225, v121, v110
	v_max3_f32 v225, v225, v111, v112
	v_max_f32_e32 v225, v225, v113
	v_mov_b32_e32 v226, v225
	s_nop 1
	v_permlane16_swap_b32_e32 v225, v226
	v_max_f32_e32 v225, v225, v226
	v_mov_b32_e32 v226, v225
	s_nop 1
	v_permlane32_swap_b32_e32 v225, v226
	v_max3_f32 v225, v246, v225, v226
	v_sub_f32_e32 v250, v246, v225
	v_sub_f32_e32 v118, v118, v225
	v_sub_f32_e32 v119, v119, v225
	v_sub_f32_e32 v120, v120, v225
	v_sub_f32_e32 v121, v121, v225
	v_sub_f32_e32 v110, v110, v225
	v_sub_f32_e32 v111, v111, v225
	v_sub_f32_e32 v112, v112, v225
	v_sub_f32_e32 v113, v113, v225
	v_exp_f32_e32 v250, v250
	v_exp_f32_e32 v118, v118
	v_exp_f32_e32 v119, v119
	v_exp_f32_e32 v120, v120
	v_exp_f32_e32 v121, v121
	v_exp_f32_e32 v110, v110
	v_exp_f32_e32 v111, v111
	v_exp_f32_e32 v112, v112
	v_exp_f32_e32 v113, v113
	v_mov_b32_e32 v246, v225
	v_add_f32_e32 v226, v118, v119
	v_add_f32_e32 v226, v226, v120
	v_add_f32_e32 v226, v226, v121
	v_add_f32_e32 v226, v226, v110
	v_add_f32_e32 v226, v226, v111
	v_add_f32_e32 v226, v226, v112
	v_add_f32_e32 v226, v226, v113
	v_fma_f32 v215, v215, v250, v226
	v_pk_mul_f32 v[16:17], v[16:17], v[250:251] op_sel_hi:[1,0]
	v_pk_mul_f32 v[14:15], v[14:15], v[250:251] op_sel_hi:[1,0]
	v_pk_mul_f32 v[12:13], v[12:13], v[250:251] op_sel_hi:[1,0]
	v_pk_mul_f32 v[10:11], v[10:11], v[250:251] op_sel_hi:[1,0]
	v_pk_mul_f32 v[8:9], v[8:9], v[250:251] op_sel_hi:[1,0]
	v_pk_mul_f32 v[6:7], v[6:7], v[250:251] op_sel_hi:[1,0]
	v_pk_mul_f32 v[4:5], v[4:5], v[250:251] op_sel_hi:[1,0]
	v_pk_mul_f32 v[2:3], v[2:3], v[250:251] op_sel_hi:[1,0]
	v_cvt_pk_bf16_f32 v118, v118, v119
	v_cvt_pk_bf16_f32 v119, v120, v121
	v_cvt_pk_bf16_f32 v120, v110, v111
	v_cvt_pk_bf16_f32 v121, v112, v113
	s_nop 1
	s_waitcnt vmcnt(11)
	v_mfma_f32_16x16x32_bf16 v[14:17], v[142:145], v[118:121], v[14:17]
	s_waitcnt vmcnt(10)
	v_mfma_f32_16x16x32_bf16 v[10:13], v[134:137], v[118:121], v[10:13]
	s_waitcnt vmcnt(9)
	v_mfma_f32_16x16x32_bf16 v[6:9], v[138:141], v[118:121], v[6:9]
	s_waitcnt vmcnt(8)
	v_mfma_f32_16x16x32_bf16 v[2:5], v[130:133], v[118:121], v[2:5]
.LBB0_556:
	s_add_i32 s90, s90, 1
	s_add_i32 s24, s36, s90
	s_add_i32 s24, s24, -1
	v_lshl_add_u64 v[174:175], v[174:175], 0, s[28:29]
	v_add_u32_e32 v219, 0x80, v219
	v_add_u32_e32 v220, 0x80, v220
	v_add_u32_e32 v221, 0x80, v221
	v_add_u32_e32 v233, 0x80, v233
	v_add_u32_e32 v234, 0x80, v234
	v_add_u32_e32 v235, 0x80, v235
	v_add_u32_e32 v236, 0x80, v236
	v_add_u32_e32 v237, 0x80, v237
	v_add_u32_e32 v238, 0x80, v238
	v_add_u32_e32 v239, 0x80, v239
	v_add_u32_e32 v240, 0x80, v240
	v_add_u32_e32 v241, 0x80, v241
	v_add_u32_e32 v242, 0x80, v242
	v_add_u32_e32 v243, 0x80, v243
	v_add_u32_e32 v244, 0x80, v244
	v_add_u32_e32 v245, 0x80, v245
	s_cmp_ge_u32 s24, s89
	v_lshl_add_u64 v[176:177], v[176:177], 0, s[62:63]
	s_cbranch_scc1 .LBB0_558
	s_waitcnt vmcnt(0)
	v_mov_b64_e32 v[110:111], v[114:115]
	v_mov_b64_e32 v[112:113], v[116:117]
	v_mov_b32_e32 v118, v106
	v_mov_b32_e32 v119, v107
	v_mov_b32_e32 v120, v108
	v_mov_b32_e32 v121, v109
	v_mov_b32_e32 v122, v102
	v_mov_b32_e32 v123, v103
	v_mov_b32_e32 v124, v104
	v_mov_b32_e32 v125, v105
	v_mov_b32_e32 v126, v98
	v_mov_b32_e32 v127, v99
	v_mov_b32_e32 v128, v100
	v_mov_b32_e32 v129, v101
	v_mov_b64_e32 v[142:143], v[200:201]
	v_mov_b64_e32 v[144:145], v[202:203]
	v_mov_b64_e32 v[134:135], v[204:205]
	v_mov_b64_e32 v[136:137], v[206:207]
	v_mov_b64_e32 v[138:139], v[208:209]
	v_mov_b64_e32 v[140:141], v[210:211]
	v_mov_b64_e32 v[130:131], v[180:181]
	v_mov_b64_e32 v[132:133], v[182:183]
	s_branch .LBB0_482
